# cache policy: SwiGLU epilogue H stores write-through (sc1) so the 92 MB hidden activation stream does not occupy the XCD L2 during gate/up
# baseline (speedup 1.0000x reference)
.LBB0_700:
	s_mov_b32 s86, 1.0
	s_lshl_b32 s5, s16, 7
	s_or_b32 s5, s5, s75
	v_add_u32_e32 v128, s5, v176
	s_lshl_b32 s5, s17, 10
	s_add_i32 s5, s5, 0
	s_add_i32 s5, s5, 0x21400
	v_lshl_add_u32 v130, v175, 2, s5
	ds_read_b32 v130, v130
	v_pk_mul_f32 v[120:121], v[124:125], v[120:121]
	v_pk_mul_f32 v[122:123], v[126:127], v[122:123]
	v_pk_mul_f32 v[112:113], v[116:117], v[112:113]
	v_pk_mul_f32 v[114:115], v[118:119], v[114:115]
	s_waitcnt lgkmcnt(0)
	v_mul_f32_e32 v131, 0xbfb8aa3b, v130
	v_pk_mul_f32 v[144:145], v[124:125], v[130:131] op_sel:[0,1] op_sel_hi:[1,1]
	v_pk_mul_f32 v[124:125], v[126:127], v[130:131] op_sel:[0,1] op_sel_hi:[1,1]
	v_exp_f32_e32 v124, v124
	v_exp_f32_e32 v125, v125
	v_exp_f32_e32 v144, v144
	v_exp_f32_e32 v145, v145
	v_pk_add_f32 v[124:125], v[124:125], s[86:87] op_sel_hi:[1,0]
	v_rcp_f32_e32 v124, v124
	v_rcp_f32_e32 v125, v125
	v_pk_add_f32 v[144:145], v[144:145], s[86:87] op_sel_hi:[1,0]
	v_rcp_f32_e32 v144, v144
	v_pk_mul_f32 v[122:123], v[122:123], v[124:125]
	v_pk_mul_f32 v[124:125], v[116:117], v[130:131] op_sel:[0,1] op_sel_hi:[1,1]
	v_exp_f32_e32 v124, v124
	v_exp_f32_e32 v125, v125
	v_pk_mul_f32 v[116:117], v[118:119], v[130:131] op_sel:[0,1] op_sel_hi:[1,1]
	v_exp_f32_e32 v116, v116
	v_exp_f32_e32 v117, v117
	v_pk_add_f32 v[124:125], v[124:125], s[86:87] op_sel_hi:[1,0]
	v_rcp_f32_e32 v124, v124
	v_rcp_f32_e32 v125, v125
	v_pk_add_f32 v[116:117], v[116:117], s[86:87] op_sel_hi:[1,0]
	v_rcp_f32_e32 v145, v145
	v_rcp_f32_e32 v116, v116
	v_rcp_f32_e32 v117, v117
	v_mul_f32_e32 v130, v130, v130
	v_pk_mul_f32 v[112:113], v[112:113], v[124:125]
	v_pk_mul_f32 v[120:121], v[120:121], v[144:145]
	v_pk_mul_f32 v[112:113], v[130:131], v[112:113] op_sel_hi:[0,1]
	v_pk_mul_f32 v[114:115], v[114:115], v[116:117]
	v_ashrrev_i32_e32 v129, 31, v128
	v_pk_mul_f32 v[120:121], v[130:131], v[120:121] op_sel_hi:[0,1]
	v_pk_mul_f32 v[114:115], v[130:131], v[114:115] op_sel_hi:[0,1]
	v_cvt_pk_bf16_f32 v118, v112, v113
	v_mov_b64_e32 v[112:113], s[36:37]
	v_pk_mul_f32 v[122:123], v[130:131], v[122:123] op_sel_hi:[0,1]
	v_cvt_pk_bf16_f32 v116, v120, v121
	v_cvt_pk_bf16_f32 v119, v114, v115
	v_mad_i64_i32 v[120:121], s[16:17], v174, s72, v[112:113]
	v_lshlrev_b64 v[114:115], 1, v[128:129]
	v_cvt_pk_bf16_f32 v117, v122, v123
	v_lshl_add_u64 v[120:121], v[120:121], 0, v[114:115]
	global_store_dwordx4 v[120:121], v[116:119], off sc1
	v_pk_mul_f32 v[104:105], v[108:109], v[104:105]
	v_pk_mul_f32 v[106:107], v[110:111], v[106:107]
	v_add_u32_e32 v117, 16, v174
	v_and_b32_e32 v116, 0xff, v117
	v_lshl_add_u32 v116, v116, 2, s5
	ds_read_b32 v116, v116
	v_pk_mul_f32 v[96:97], v[100:101], v[96:97]
	v_pk_mul_f32 v[98:99], v[102:103], v[98:99]
	v_pk_mul_f32 v[88:89], v[92:93], v[88:89]
	v_pk_mul_f32 v[90:91], v[94:95], v[90:91]
	s_waitcnt lgkmcnt(0)
	v_mul_f32_e32 v120, 0xbfb8aa3b, v116
	v_pk_mul_f32 v[118:119], v[108:109], v[120:121] op_sel_hi:[1,0]
	v_pk_mul_f32 v[108:109], v[110:111], v[120:121] op_sel_hi:[1,0]
	v_exp_f32_e32 v108, v108
	v_exp_f32_e32 v109, v109
	v_mul_f32_e32 v116, v116, v116
	v_exp_f32_e32 v118, v118
	v_pk_add_f32 v[108:109], v[108:109], s[86:87] op_sel_hi:[1,0]
	v_rcp_f32_e32 v108, v108
	v_rcp_f32_e32 v109, v109
	v_exp_f32_e32 v119, v119
	v_add_f32_e32 v118, 1.0, v118
	v_rcp_f32_e32 v118, v118
	v_pk_mul_f32 v[106:107], v[106:107], v[108:109]
	v_pk_mul_f32 v[108:109], v[100:101], v[120:121] op_sel_hi:[1,0]
	v_exp_f32_e32 v108, v108
	v_exp_f32_e32 v109, v109
	v_add_f32_e32 v119, 1.0, v119
	v_rcp_f32_e32 v119, v119
	v_pk_add_f32 v[108:109], v[108:109], s[86:87] op_sel_hi:[1,0]
	v_rcp_f32_e32 v108, v108
	v_rcp_f32_e32 v109, v109
	v_pk_mul_f32 v[104:105], v[104:105], v[118:119]
	v_pk_mul_f32 v[106:107], v[116:117], v[106:107] op_sel_hi:[0,1]
	v_pk_mul_f32 v[104:105], v[116:117], v[104:105] op_sel_hi:[0,1]
	v_pk_mul_f32 v[96:97], v[96:97], v[108:109]
	v_pk_mul_f32 v[80:81], v[84:85], v[80:81]
	v_pk_mul_f32 v[100:101], v[116:117], v[96:97] op_sel_hi:[0,1]
	v_pk_mul_f32 v[96:97], v[102:103], v[120:121] op_sel_hi:[1,0]
	v_exp_f32_e32 v96, v96
	v_exp_f32_e32 v97, v97
	v_pk_mul_f32 v[82:83], v[86:87], v[82:83]
	v_pk_mul_f32 v[72:73], v[76:77], v[72:73]
	v_pk_add_f32 v[96:97], v[96:97], s[86:87] op_sel_hi:[1,0]
	v_rcp_f32_e32 v96, v96
	v_rcp_f32_e32 v97, v97
	v_pk_mul_f32 v[74:75], v[78:79], v[74:75]
	v_pk_mul_f32 v[64:65], v[68:69], v[64:65]
	v_pk_mul_f32 v[66:67], v[70:71], v[66:67]
	v_pk_mul_f32 v[96:97], v[98:99], v[96:97]
	v_cvt_pk_bf16_f32 v98, v100, v101
	v_pk_mul_f32 v[102:103], v[116:117], v[96:97] op_sel_hi:[0,1]
	v_mad_i64_i32 v[100:101], s[16:17], v117, s72, v[112:113]
	v_cvt_pk_bf16_f32 v96, v104, v105
	v_cvt_pk_bf16_f32 v97, v106, v107
	v_cvt_pk_bf16_f32 v99, v102, v103
	v_lshl_add_u64 v[100:101], v[100:101], 0, v[114:115]
	global_store_dwordx4 v[100:101], v[96:99], off sc1
	v_pk_mul_f32 v[56:57], v[60:61], v[56:57]
	v_pk_mul_f32 v[58:59], v[62:63], v[58:59]
	v_add_u32_e32 v97, 32, v174
	v_and_b32_e32 v96, 0xff, v97
	v_lshl_add_u32 v96, v96, 2, s5
	ds_read_b32 v96, v96
	v_pk_mul_f32 v[48:49], v[52:53], v[48:49]
	v_pk_mul_f32 v[50:51], v[54:55], v[50:51]
	v_pk_mul_f32 v[40:41], v[44:45], v[40:41]
	v_pk_mul_f32 v[42:43], v[46:47], v[42:43]
	s_waitcnt lgkmcnt(0)
	v_mul_f32_e32 v100, 0xbfb8aa3b, v96
	v_pk_mul_f32 v[98:99], v[92:93], v[100:101] op_sel_hi:[1,0]
	v_pk_mul_f32 v[92:93], v[94:95], v[100:101] op_sel_hi:[1,0]
	v_exp_f32_e32 v92, v92
	v_exp_f32_e32 v93, v93
	v_mul_f32_e32 v96, v96, v96
	v_exp_f32_e32 v98, v98
	v_pk_add_f32 v[92:93], v[92:93], s[86:87] op_sel_hi:[1,0]
	v_rcp_f32_e32 v92, v92
	v_rcp_f32_e32 v93, v93
	v_exp_f32_e32 v99, v99
	v_add_f32_e32 v98, 1.0, v98
	v_rcp_f32_e32 v98, v98
	v_pk_mul_f32 v[90:91], v[90:91], v[92:93]
	v_pk_mul_f32 v[92:93], v[84:85], v[100:101] op_sel_hi:[1,0]
	v_exp_f32_e32 v92, v92
	v_exp_f32_e32 v93, v93
	v_add_f32_e32 v99, 1.0, v99
	v_rcp_f32_e32 v99, v99
	v_pk_add_f32 v[92:93], v[92:93], s[86:87] op_sel_hi:[1,0]
	v_rcp_f32_e32 v92, v92
	v_rcp_f32_e32 v93, v93
	v_pk_mul_f32 v[88:89], v[88:89], v[98:99]
	v_pk_mul_f32 v[90:91], v[96:97], v[90:91] op_sel_hi:[0,1]
	v_pk_mul_f32 v[88:89], v[96:97], v[88:89] op_sel_hi:[0,1]
	v_pk_mul_f32 v[80:81], v[80:81], v[92:93]
	v_pk_mul_f32 v[32:33], v[36:37], v[32:33]
	v_pk_mul_f32 v[84:85], v[96:97], v[80:81] op_sel_hi:[0,1]
	v_pk_mul_f32 v[80:81], v[86:87], v[100:101] op_sel_hi:[1,0]
	v_exp_f32_e32 v80, v80
	v_exp_f32_e32 v81, v81
	v_pk_mul_f32 v[34:35], v[38:39], v[34:35]
	v_pk_mul_f32 v[24:25], v[28:29], v[24:25]
	v_pk_add_f32 v[80:81], v[80:81], s[86:87] op_sel_hi:[1,0]
	v_rcp_f32_e32 v80, v80
	v_rcp_f32_e32 v81, v81
	v_pk_mul_f32 v[26:27], v[30:31], v[26:27]
	v_pk_mul_f32 v[16:17], v[20:21], v[16:17]
	v_pk_mul_f32 v[18:19], v[22:23], v[18:19]
	v_pk_mul_f32 v[80:81], v[82:83], v[80:81]
	v_cvt_pk_bf16_f32 v82, v84, v85
	v_pk_mul_f32 v[86:87], v[96:97], v[80:81] op_sel_hi:[0,1]
	v_mad_i64_i32 v[84:85], s[16:17], v97, s72, v[112:113]
	v_cvt_pk_bf16_f32 v80, v88, v89
	v_cvt_pk_bf16_f32 v81, v90, v91
	v_cvt_pk_bf16_f32 v83, v86, v87
	v_lshl_add_u64 v[84:85], v[84:85], 0, v[114:115]
	global_store_dwordx4 v[84:85], v[80:83], off sc1
	v_pk_mul_f32 v[0:1], v[4:5], v[0:1]
	v_pk_mul_f32 v[14:15], v[10:11], v[14:15]
	v_add_u32_e32 v81, 48, v174
	v_and_b32_e32 v80, 0xff, v81
	v_lshl_add_u32 v80, v80, 2, s5
	ds_read_b32 v80, v80
	v_pk_mul_f32 v[2:3], v[6:7], v[2:3]
	s_waitcnt lgkmcnt(0)
	v_mul_f32_e32 v84, 0xbfb8aa3b, v80
	v_pk_mul_f32 v[82:83], v[76:77], v[84:85] op_sel_hi:[1,0]
	v_pk_mul_f32 v[76:77], v[78:79], v[84:85] op_sel_hi:[1,0]
	v_exp_f32_e32 v76, v76
	v_exp_f32_e32 v77, v77
	v_mul_f32_e32 v80, v80, v80
	v_exp_f32_e32 v82, v82
	v_pk_add_f32 v[76:77], v[76:77], s[86:87] op_sel_hi:[1,0]
	v_rcp_f32_e32 v76, v76
	v_rcp_f32_e32 v77, v77
	v_exp_f32_e32 v83, v83
	v_add_f32_e32 v82, 1.0, v82
	v_rcp_f32_e32 v82, v82
	v_pk_mul_f32 v[74:75], v[74:75], v[76:77]
	v_pk_mul_f32 v[76:77], v[68:69], v[84:85] op_sel_hi:[1,0]
	v_exp_f32_e32 v76, v76
	v_exp_f32_e32 v77, v77
	v_add_f32_e32 v83, 1.0, v83
	v_rcp_f32_e32 v83, v83
	v_pk_add_f32 v[76:77], v[76:77], s[86:87] op_sel_hi:[1,0]
	v_rcp_f32_e32 v76, v76
	v_rcp_f32_e32 v77, v77
	v_pk_mul_f32 v[72:73], v[72:73], v[82:83]
	v_pk_mul_f32 v[74:75], v[80:81], v[74:75] op_sel_hi:[0,1]
	v_pk_mul_f32 v[72:73], v[80:81], v[72:73] op_sel_hi:[0,1]
	v_pk_mul_f32 v[64:65], v[64:65], v[76:77]
	s_nop 0
	v_pk_mul_f32 v[68:69], v[80:81], v[64:65] op_sel_hi:[0,1]
	v_pk_mul_f32 v[64:65], v[70:71], v[84:85] op_sel_hi:[1,0]
	v_exp_f32_e32 v64, v64
	v_exp_f32_e32 v65, v65
	s_nop 0
	v_pk_add_f32 v[64:65], v[64:65], s[86:87] op_sel_hi:[1,0]
	v_rcp_f32_e32 v64, v64
	v_rcp_f32_e32 v65, v65
	s_nop 0
	v_pk_mul_f32 v[64:65], v[66:67], v[64:65]
	s_nop 0
	v_pk_mul_f32 v[70:71], v[80:81], v[64:65] op_sel_hi:[0,1]
	v_cvt_pk_bf16_f32 v66, v68, v69
	v_mad_i64_i32 v[68:69], s[16:17], v81, s72, v[112:113]
	v_cvt_pk_bf16_f32 v64, v72, v73
	v_cvt_pk_bf16_f32 v65, v74, v75
	v_cvt_pk_bf16_f32 v67, v70, v71
	v_lshl_add_u64 v[68:69], v[68:69], 0, v[114:115]
	global_store_dwordx4 v[68:69], v[64:67], off sc1
	s_nop 1
	v_add_u32_e32 v65, 0x80, v174
	v_and_b32_e32 v64, 0xff, v65
	v_lshl_add_u32 v64, v64, 2, s5
	ds_read_b32 v64, v64
	s_waitcnt lgkmcnt(0)
	v_mul_f32_e32 v68, 0xbfb8aa3b, v64
	v_pk_mul_f32 v[66:67], v[60:61], v[68:69] op_sel_hi:[1,0]
	v_pk_mul_f32 v[60:61], v[62:63], v[68:69] op_sel_hi:[1,0]
	v_exp_f32_e32 v60, v60
	v_exp_f32_e32 v61, v61
	v_mul_f32_e32 v64, v64, v64
	v_exp_f32_e32 v66, v66
	v_pk_add_f32 v[60:61], v[60:61], s[86:87] op_sel_hi:[1,0]
	v_rcp_f32_e32 v60, v60
	v_rcp_f32_e32 v61, v61
	v_exp_f32_e32 v67, v67
	v_add_f32_e32 v66, 1.0, v66
	v_rcp_f32_e32 v66, v66
	v_pk_mul_f32 v[58:59], v[58:59], v[60:61]
	v_pk_mul_f32 v[60:61], v[52:53], v[68:69] op_sel_hi:[1,0]
	v_exp_f32_e32 v60, v60
	v_exp_f32_e32 v61, v61
	v_add_f32_e32 v67, 1.0, v67
	v_rcp_f32_e32 v67, v67
	v_pk_add_f32 v[60:61], v[60:61], s[86:87] op_sel_hi:[1,0]
	v_rcp_f32_e32 v60, v60
	v_rcp_f32_e32 v61, v61
	v_pk_mul_f32 v[56:57], v[56:57], v[66:67]
	v_pk_mul_f32 v[58:59], v[64:65], v[58:59] op_sel_hi:[0,1]
	v_pk_mul_f32 v[56:57], v[64:65], v[56:57] op_sel_hi:[0,1]
	v_pk_mul_f32 v[48:49], v[48:49], v[60:61]
	s_nop 0
	v_pk_mul_f32 v[52:53], v[64:65], v[48:49] op_sel_hi:[0,1]
	v_pk_mul_f32 v[48:49], v[54:55], v[68:69] op_sel_hi:[1,0]
	v_exp_f32_e32 v48, v48
	v_exp_f32_e32 v49, v49
	s_nop 0
	v_pk_add_f32 v[48:49], v[48:49], s[86:87] op_sel_hi:[1,0]
	v_rcp_f32_e32 v48, v48
	v_rcp_f32_e32 v49, v49
	s_nop 0
	v_pk_mul_f32 v[48:49], v[50:51], v[48:49]
	s_nop 0
	v_pk_mul_f32 v[54:55], v[64:65], v[48:49] op_sel_hi:[0,1]
	v_cvt_pk_bf16_f32 v50, v52, v53
	v_mad_i64_i32 v[52:53], s[16:17], v65, s72, v[112:113]
	v_cvt_pk_bf16_f32 v48, v56, v57
	v_cvt_pk_bf16_f32 v49, v58, v59
	v_cvt_pk_bf16_f32 v51, v54, v55
	v_lshl_add_u64 v[52:53], v[52:53], 0, v[114:115]
	global_store_dwordx4 v[52:53], v[48:51], off sc1
	s_nop 1
	v_add_u32_e32 v49, 0x90, v174
	v_and_b32_e32 v48, 0xff, v49
	v_lshl_add_u32 v48, v48, 2, s5
	ds_read_b32 v48, v48
	s_waitcnt lgkmcnt(0)
	v_mul_f32_e32 v52, 0xbfb8aa3b, v48
	v_pk_mul_f32 v[50:51], v[44:45], v[52:53] op_sel_hi:[1,0]
	v_pk_mul_f32 v[44:45], v[46:47], v[52:53] op_sel_hi:[1,0]
	v_exp_f32_e32 v44, v44
	v_exp_f32_e32 v45, v45
	v_mul_f32_e32 v48, v48, v48
	v_exp_f32_e32 v50, v50
	v_pk_add_f32 v[44:45], v[44:45], s[86:87] op_sel_hi:[1,0]
	v_rcp_f32_e32 v44, v44
	v_rcp_f32_e32 v45, v45
	v_exp_f32_e32 v51, v51
	v_add_f32_e32 v50, 1.0, v50
	v_rcp_f32_e32 v50, v50
	v_pk_mul_f32 v[42:43], v[42:43], v[44:45]
	v_pk_mul_f32 v[44:45], v[36:37], v[52:53] op_sel_hi:[1,0]
	v_exp_f32_e32 v44, v44
	v_exp_f32_e32 v45, v45
	v_add_f32_e32 v51, 1.0, v51
	v_rcp_f32_e32 v51, v51
	v_pk_add_f32 v[44:45], v[44:45], s[86:87] op_sel_hi:[1,0]
	v_rcp_f32_e32 v44, v44
	v_rcp_f32_e32 v45, v45
	v_pk_mul_f32 v[40:41], v[40:41], v[50:51]
	v_pk_mul_f32 v[42:43], v[48:49], v[42:43] op_sel_hi:[0,1]
	v_pk_mul_f32 v[40:41], v[48:49], v[40:41] op_sel_hi:[0,1]
	v_pk_mul_f32 v[32:33], v[32:33], v[44:45]
	s_nop 0
	v_pk_mul_f32 v[36:37], v[48:49], v[32:33] op_sel_hi:[0,1]
	v_pk_mul_f32 v[32:33], v[38:39], v[52:53] op_sel_hi:[1,0]
	v_exp_f32_e32 v32, v32
	v_exp_f32_e32 v33, v33
	s_nop 0
	v_pk_add_f32 v[32:33], v[32:33], s[86:87] op_sel_hi:[1,0]
	v_rcp_f32_e32 v32, v32
	v_rcp_f32_e32 v33, v33
	s_nop 0
	v_pk_mul_f32 v[32:33], v[34:35], v[32:33]
	s_nop 0
	v_pk_mul_f32 v[38:39], v[48:49], v[32:33] op_sel_hi:[0,1]
	v_cvt_pk_bf16_f32 v34, v36, v37
	v_mad_i64_i32 v[36:37], s[16:17], v49, s72, v[112:113]
	v_cvt_pk_bf16_f32 v32, v40, v41
	v_cvt_pk_bf16_f32 v33, v42, v43
	v_cvt_pk_bf16_f32 v35, v38, v39
	v_lshl_add_u64 v[36:37], v[36:37], 0, v[114:115]
	global_store_dwordx4 v[36:37], v[32:35], off sc1
	s_nop 1
	v_add_u32_e32 v33, 0xa0, v174
	v_and_b32_e32 v32, 0xff, v33
	v_lshl_add_u32 v32, v32, 2, s5
	ds_read_b32 v32, v32
	s_waitcnt lgkmcnt(0)
	v_mul_f32_e32 v36, 0xbfb8aa3b, v32
	v_pk_mul_f32 v[34:35], v[28:29], v[36:37] op_sel_hi:[1,0]
	v_pk_mul_f32 v[28:29], v[30:31], v[36:37] op_sel_hi:[1,0]
	v_exp_f32_e32 v28, v28
	v_exp_f32_e32 v29, v29
	v_mul_f32_e32 v32, v32, v32
	v_exp_f32_e32 v34, v34
	v_pk_add_f32 v[28:29], v[28:29], s[86:87] op_sel_hi:[1,0]
	v_rcp_f32_e32 v28, v28
	v_rcp_f32_e32 v29, v29
	v_exp_f32_e32 v35, v35
	v_add_f32_e32 v34, 1.0, v34
	v_rcp_f32_e32 v34, v34
	v_pk_mul_f32 v[26:27], v[26:27], v[28:29]
	v_pk_mul_f32 v[28:29], v[20:21], v[36:37] op_sel_hi:[1,0]
	v_exp_f32_e32 v28, v28
	v_exp_f32_e32 v29, v29
	v_add_f32_e32 v35, 1.0, v35
	v_rcp_f32_e32 v35, v35
	v_pk_add_f32 v[28:29], v[28:29], s[86:87] op_sel_hi:[1,0]
	v_rcp_f32_e32 v28, v28
	v_rcp_f32_e32 v29, v29
	v_pk_mul_f32 v[24:25], v[24:25], v[34:35]
	v_pk_mul_f32 v[26:27], v[32:33], v[26:27] op_sel_hi:[0,1]
	v_pk_mul_f32 v[24:25], v[32:33], v[24:25] op_sel_hi:[0,1]
	v_pk_mul_f32 v[16:17], v[16:17], v[28:29]
	s_nop 0
	v_pk_mul_f32 v[20:21], v[32:33], v[16:17] op_sel_hi:[0,1]
	v_pk_mul_f32 v[16:17], v[22:23], v[36:37] op_sel_hi:[1,0]
	v_exp_f32_e32 v16, v16
	v_exp_f32_e32 v17, v17
	s_nop 0
	v_pk_add_f32 v[16:17], v[16:17], s[86:87] op_sel_hi:[1,0]
	v_rcp_f32_e32 v16, v16
	v_rcp_f32_e32 v17, v17
	s_nop 0
	v_pk_mul_f32 v[16:17], v[18:19], v[16:17]
	s_nop 0
	v_pk_mul_f32 v[22:23], v[32:33], v[16:17] op_sel_hi:[0,1]
	v_cvt_pk_bf16_f32 v18, v20, v21
	v_mad_i64_i32 v[20:21], s[16:17], v33, s72, v[112:113]
	v_cvt_pk_bf16_f32 v16, v24, v25
	v_cvt_pk_bf16_f32 v17, v26, v27
	v_cvt_pk_bf16_f32 v19, v22, v23
	v_lshl_add_u64 v[20:21], v[20:21], 0, v[114:115]
	global_store_dwordx4 v[20:21], v[16:19], off sc1
	s_nop 1
	v_add_u32_e32 v16, 0xb0, v174
	v_and_b32_e32 v17, 0xff, v16
	v_lshl_add_u32 v17, v17, 2, s5
	ds_read_b32 v17, v17
	s_waitcnt lgkmcnt(0)
	v_mul_f32_e32 v19, 0xbfb8aa3b, v17
	v_mul_f32_e32 v18, v17, v17
	v_mul_f32_e32 v17, v8, v19
	v_exp_f32_e32 v17, v17
	v_pk_mul_f32 v[10:11], v[10:11], v[18:19] op_sel:[0,1] op_sel_hi:[1,1]
	v_exp_f32_e32 v10, v10
	v_add_f32_e32 v17, 1.0, v17
	v_rcp_f32_e32 v20, v17
	v_mul_f32_e32 v17, v9, v19
	v_pk_mul_f32 v[8:9], v[8:9], v[12:13]
	v_pk_mul_f32 v[12:13], v[4:5], v[18:19] op_sel:[0,1] op_sel_hi:[1,1]
	v_exp_f32_e32 v12, v12
	v_exp_f32_e32 v13, v13
	v_exp_f32_e32 v17, v17
	v_exp_f32_e32 v11, v11
	v_pk_add_f32 v[12:13], v[12:13], s[86:87] op_sel_hi:[1,0]
	v_rcp_f32_e32 v12, v12
	v_rcp_f32_e32 v13, v13
	v_add_f32_e32 v17, 1.0, v17
	v_pk_add_f32 v[10:11], v[10:11], s[86:87] op_sel_hi:[1,0]
	v_pk_mul_f32 v[0:1], v[0:1], v[12:13]
	v_rcp_f32_e32 v21, v17
	v_pk_mul_f32 v[4:5], v[18:19], v[0:1] op_sel_hi:[0,1]
	v_pk_mul_f32 v[0:1], v[6:7], v[18:19] op_sel:[0,1] op_sel_hi:[1,1]
	v_exp_f32_e32 v0, v0
	v_exp_f32_e32 v1, v1
	v_rcp_f32_e32 v10, v10
	v_rcp_f32_e32 v11, v11
	v_pk_add_f32 v[0:1], v[0:1], s[86:87] op_sel_hi:[1,0]
	v_rcp_f32_e32 v0, v0
	v_rcp_f32_e32 v1, v1
	v_pk_mul_f32 v[8:9], v[8:9], v[20:21]
	v_pk_mul_f32 v[10:11], v[14:15], v[10:11]
	v_pk_mul_f32 v[8:9], v[18:19], v[8:9] op_sel_hi:[0,1]
	v_pk_mul_f32 v[0:1], v[2:3], v[0:1]
	v_pk_mul_f32 v[10:11], v[18:19], v[10:11] op_sel_hi:[0,1]
	v_pk_mul_f32 v[6:7], v[18:19], v[0:1] op_sel_hi:[0,1]
	v_cvt_pk_bf16_f32 v2, v4, v5
	v_mad_i64_i32 v[4:5], s[16:17], v16, s72, v[112:113]
	v_cvt_pk_bf16_f32 v0, v8, v9
	v_cvt_pk_bf16_f32 v1, v10, v11
	v_cvt_pk_bf16_f32 v3, v6, v7
	v_lshl_add_u64 v[4:5], v[4:5], 0, v[114:115]
	global_store_dwordx4 v[4:5], v[0:3], off sc1
	s_andn2_b64 vcc, exec, s[38:39]
	s_mov_b64 s[16:17], -1
	s_cbranch_vccnz .LBB0_625
